# gate/up GEMM SwiGLU epilogue: per-row RMS sums loaded at unit set-up (fin pointer via one scalar load per GEMM), no blocking loads after the K-loop
# speedup vs baseline: 1.0001x; 1.0001x over previous
;     __host__ __device__ bool next(int i, Unit& u) const {
;         const long L = (long)i * G + c; if (L >= nwg) return false;
;         int wgid = (int)L; { const int q = nwg / NXCD, r = nwg % NXCD, xcd = wgid % NXCD, off = wgid / NXCD; wgid = (xcd < r ? xcd * (q + 1) : r * (q + 1) + (xcd - r) * q) + off; }
;         const int nig = WGM * nN, gid = wgid / nig, fm = gid * WGM, gsz = (nM - fm) < WGM ? (nM - fm) : WGM;
;         u.pm = fm + ((wgid % nig) % gsz); u.pn = (wgid % nig) / gsz; return true;
; __global__ void __launch_bounds__(NTHR, 2) hymba_fwd(KArgs a) {
;     ...
;             const EpiP* egp = (const EpiP*)(ws + WS_CTL + 1024) + (l * 12 + ((f && gid0 + j < 2) ? 10 + gid0 + j : gid0 + j));
;     ...
;             pg8::StaticOrder S; S.init(d.M, d.N, G, (int)((bid + d.rot) % G));
;     ...
;             if (d.K == 1024) { pg8::Gemm gk{d.A, d.Bt, d.M, d.N, 1024}; EpiGenT<true> eg; eg.p = egp; pg8::gemm_phase<EpiGenT<true>, pg8::StaticOrder, true, true>(lds, gk, S, eg, wave0); }
.LBB0_1007:
	s_cmp_gt_u32 s4, 1
	s_cselect_b64 s[2:3], -1, 0
	s_or_b64 s[2:3], s[14:15], s[2:3]
	s_add_i32 s6, s4, 10
	s_and_b64 s[2:3], s[2:3], exec
	s_cselect_b32 s2, s4, s6
	s_add_i32 s80, s2, s34
	s_lshl_b64 s[2:3], s[80:81], 6
	s_add_u32 s40, s8, s2
	v_readlane_b32 s2, v254, 43
	s_addc_u32 s41, s9, s3
	s_load_dwordx2 s[98:99], s[40:41], 0x418
	s_add_i32 s2, s5, s2
	s_ashr_i32 s3, s2, 31
	s_abs_i32 s2, s2
	v_readlane_b32 s4, v253, 59
	s_mul_hi_u32 s4, s2, s4
	v_readlane_b32 s5, v253, 58
	s_mul_i32 s4, s4, s5
	s_sub_i32 s2, s2, s4
	s_sub_i32 s4, s2, s5
	s_cmp_ge_u32 s2, s5
	s_cselect_b32 s2, s4, s2
	s_sub_i32 s4, s2, s5
	s_cmp_ge_u32 s2, s5
	s_cselect_b32 s2, s4, s2
	s_xor_b32 s2, s2, s3
	s_sub_i32 s21, s2, s3
	s_mul_i32 s42, s35, s20
	s_mov_b64 s[44:45], -1
	s_mov_b64 s[12:13], 0
	s_cmpk_lt_i32 s22, 0x400
	s_mov_b64 s[2:3], 0
	s_cbranch_scc1 .LBB0_1244
	s_cmpk_gt_i32 s22, 0xaff
	s_mov_b64 s[2:3], -1
	s_cbranch_scc0 .LBB0_1127
	s_cmp_lt_i32 s21, s42
	v_mov_b32_e32 v8, v246
	s_cselect_b64 s[2:3], -1, 0
	s_cmp_ge_i32 s21, s42
	s_cbranch_scc1 .LBB0_1011
	s_lshl_b32 s7, s20, 3
	v_cvt_f32_u32_e32 v0, s7
	s_ashr_i32 s5, s21, 31
	s_lshr_b32 s5, s5, 29
	s_add_i32 s5, s21, s5
	v_rcp_iflag_f32_e32 v0, v0
	s_ashr_i32 s6, s5, 3
	s_and_b32 s5, s5, -8
	s_sub_i32 s5, s21, s5
	v_mul_f32_e32 v0, 0x4f7ffffe, v0
	v_cvt_u32_f32_e32 v0, v0
	s_lshr_b32 s4, s42, 3
	s_lshr_b32 s8, s5, 31
	s_or_b32 s4, s4, s8
	s_sub_i32 s8, 0, s7
	v_readfirstlane_b32 s9, v0
	s_mul_i32 s4, s5, s4
	s_mul_i32 s8, s8, s9
	s_add_i32 s4, s4, s6
	s_mul_hi_u32 s8, s9, s8
	s_abs_i32 s6, s4
	s_add_i32 s9, s9, s8
	s_mul_hi_u32 s8, s6, s9
	s_mul_i32 s9, s8, s7
	s_sub_i32 s6, s6, s9
	s_ashr_i32 s5, s4, 31
	s_add_i32 s9, s8, 1
	s_sub_i32 s10, s6, s7
	s_cmp_ge_u32 s6, s7
	s_cselect_b32 s8, s9, s8
	s_cselect_b32 s6, s10, s6
	s_add_i32 s9, s8, 1
	s_cmp_ge_u32 s6, s7
	s_cselect_b32 s6, s9, s8
	s_xor_b32 s6, s6, s5
	s_sub_i32 s5, s6, s5
	s_lshl_b32 s6, s5, 3
	s_sub_i32 s8, s35, s6
	s_min_i32 s8, s8, 8
	s_mul_i32 s5, s5, s7
	s_sext_i32_i16 s7, s8
	v_cvt_f32_i32_e32 v0, s7
	s_sub_i32 s9, s4, s5
	s_sext_i32_i16 s4, s9
	v_cvt_f32_i32_e32 v1, s4
	v_rcp_iflag_f32_e32 v2, v0
	s_xor_b32 s4, s4, s7
	s_ashr_i32 s4, s4, 30
	s_or_b32 s7, s4, 1
	v_mul_f32_e32 v2, v1, v2
	v_trunc_f32_e32 v2, v2
	v_fma_f32 v1, -v2, v0, v1
	v_cvt_i32_f32_e32 v2, v2
	v_cmp_ge_f32_e64 s[4:5], |v1|, |v0|
	s_and_b64 s[4:5], s[4:5], exec
	s_cselect_b32 s4, s7, 0
	v_readfirstlane_b32 s5, v2
	s_add_i32 s4, s5, s4
	s_sext_i32_i16 s55, s4
	s_mul_i32 s4, s4, s8
	s_sub_i32 s4, s9, s4
	s_sext_i32_i16 s4, s4
	s_add_i32 s56, s6, s4

; #define PG8_STAGE(bufoff, gbase, voff) do { _Pragma("unroll") for (int _i = 0; _i < 2; ++_i) \
;         __builtin_amdgcn_global_load_lds((const unsigned*)((const char*)(gbase) + (voff)[_i]), (PG8_LAS unsigned*)(lds + (bufoff) + ldsw + _i * 8192), 16, 0, 0); } while (0)
; #define PG8_LDA(dst, b, h) do { _Pragma("unroll") for (int m = 0; m < 4; ++m) _Pragma("unroll") for (int k = 0; k < 2; ++k) dst[m][k] = *(const PG8_LAS bf16x8*)(lds + PG8_SA(b, h) + aoff + m * 2048 + k * 1024); } while (0)
; #define PG8_LDB(dst, b, h) do { _Pragma("unroll") for (int n = 0; n < 2; ++n) _Pragma("unroll") for (int k = 0; k < 2; ++k) dst[n][k] = *(const PG8_LAS bf16x8*)(lds + PG8_SB(b, h) + boff + n * 2048 + k * 1024); } while (0)
; template <class Epi, class Sched, bool ALIGN_EPI = false, bool SP2 = false>
; __device__ __forceinline__ void gemm_phase(PG8_LAS unsigned char* lds, const Gemm g, const Sched& S, const Epi& E, const int wave0) {
;     ...
;     for (;;) {
;         const bool has_next = S.next(ui + 1, nxt);
;         const char* nA = has_next ? (const char*)g.A + (size_t)nxt.pm * tstep : cA; const char* nB = has_next ? (const char*)g.Bt + (size_t)nxt.pn * tstep : cB;
;         for (int t = 0; t < nt; t += 2) {
;             const bool last = (t == nt - 2);
;             const char* a1 = cA + (size_t)(t + 1) * kstep;
;             const char* a2 = last ? nA : cA + (size_t)(t + 2) * kstep; const char* b2 = last ? nB : cB + (size_t)(t + 2) * kstep;
;             const char* a3 = a2 + kstep; const char* b3 = b2 + kstep;
;             if (last && has_next) S.a_ready(nxt);
;             if constexpr (SP2) {
;             PG8_LDB(B0, 0, 0); PG8_LDB(B1, 0, 1); PG8_SCHED; PG8_LDA(At, 0, 0); PG8_STAGE(PG8_SA(1, 1), a1 + hstep, voffA);
;             PG8_WAIT_V(8); PG8_WAIT_L(0); PG8_BAR; PG8_MMA(0, 0, At, B0); PG8_MMA(0, 1, At, B1); PG8_BAR; PG8_SCHED;
;             PG8_LDA(At, 0, 1); PG8_STAGE(PG8_SB(0, 0), b2, voffB); PG8_STAGE(PG8_SB(0, 1), b2 + hstep, voffB); PG8_STAGE(PG8_SA(0, 0), a2, voffA);
;     __device__ __forceinline__ void operator()(const pg8::f32x4 (&acc)[2][2][4][2], const pg8::Unit& u, int wr, int wc, int fr, int fq) const {
;     ...
;         if (kind == EK_ACT) {
;             float rsv[2][4];
; #pragma unroll
;             for (int ai = 0; ai < 2; ++ai)
; #pragma unroll
;                 for (int m = 0; m < 4; ++m) rsv[ai][m] = fin[rowb + 128 * ai + 16 * m];
.LBB0_1139:
	s_ashr_i32 s49, s48, 31
	s_lshl_b64 s[18:19], s[48:49], 19
	s_add_u32 s50, s36, s18
	s_addc_u32 s51, s37, s19
	s_and_b64 s[18:19], s[6:7], exec
	s_cselect_b32 s9, s51, s11
	s_cselect_b32 s49, s50, s10
	s_ashr_i32 s47, s46, 31
	s_lshl_b64 s[18:19], s[46:47], 19
	s_add_u32 s52, s38, s18
	s_addc_u32 s53, s39, s19
	s_and_b64 s[18:19], s[6:7], exec
	s_cselect_b32 s47, s53, s57
	s_cselect_b32 s60, s52, s56
	s_add_u32 s10, s10, 0x40080
	s_addc_u32 s11, s11, 0
	s_add_u32 s61, s56, 0x100
	s_addc_u32 s62, s57, 0
	s_mov_b32 s63, -2
	global_load_dwordx4 v[192:195], v215, s[40:41] offset:1024
	global_load_dwordx4 v[196:199], v215, s[40:41] offset:1064
	global_load_dwordx4 v[200:203], v215, s[40:41] offset:1048
	s_waitcnt lgkmcnt(0)
	v_lshl_add_u32 v212, s8, 8, v252
	v_ashrrev_i32_e32 v213, 31, v212
	v_lshl_add_u64 v[212:213], v[212:213], 2, s[98:99]
	global_load_dword v204, v[212:213], off
	global_load_dword v205, v[212:213], off offset:64
	global_load_dword v206, v[212:213], off offset:128
	global_load_dword v207, v[212:213], off offset:192
	global_load_dword v208, v[212:213], off offset:512
	global_load_dword v209, v[212:213], off offset:576
	global_load_dword v210, v[212:213], off offset:640
	global_load_dword v211, v[212:213], off offset:704
	s_add_u32 s18, s10, 0xfffc0080
	s_addc_u32 s19, s11, -1
	s_add_i32 s64, 0, 0x10000
	s_cmp_eq_u32 s63, 12
	s_cselect_b32 s59, s9, s19
	s_cselect_b32 s58, s49, s18
	s_cselect_b32 s57, s47, s62
	s_cselect_b32 s56, s60, s61
	s_add_i32 s65, 0, 0x14000
	v_add_u32_e32 v140, s64, v247
	v_add_u32_e32 v156, s65, v247
	ds_read_b128 v[64:67], v140
	ds_read_b128 v[68:71], v140 offset:1024
	ds_read_b128 v[136:139], v140 offset:2048
	ds_read_b128 v[140:143], v140 offset:3072
	ds_read_b128 v[144:147], v156
	ds_read_b128 v[148:151], v156 offset:1024
	ds_read_b128 v[152:155], v156 offset:2048
	ds_read_b128 v[156:159], v156 offset:3072
	s_add_i32 m0, s33, 0xc000
	ds_read_b128 v[160:163], v245
	ds_read_b128 v[164:167], v245 offset:1024
	ds_read_b128 v[168:171], v245 offset:2048
	ds_read_b128 v[172:175], v245 offset:3072
	ds_read_b128 v[176:179], v245 offset:4096
	ds_read_b128 v[180:183], v245 offset:5120
	ds_read_b128 v[184:187], v245 offset:6144
	ds_read_b128 v[188:191], v245 offset:7168
	global_load_lds_dwordx4 v224, s[10:11]
	s_add_i32 m0, s33, 0xe000
	s_nop 0
	global_load_lds_dwordx4 v226, s[10:11]
	s_waitcnt vmcnt(8)
	s_waitcnt lgkmcnt(0)
	s_barrier
	s_setprio 1
	v_mfma_f32_16x16x32_bf16 v[132:135], v[64:67], v[160:163], 0
	v_mfma_f32_16x16x32_bf16 v[128:131], v[136:139], v[160:163], 0
	v_mfma_f32_16x16x32_bf16 v[116:119], v[64:67], v[168:171], 0
	v_mfma_f32_16x16x32_bf16 v[108:111], v[136:139], v[168:171], 0
	v_mfma_f32_16x16x32_bf16 v[100:103], v[64:67], v[176:179], 0
	v_mfma_f32_16x16x32_bf16 v[92:95], v[136:139], v[176:179], 0
	v_mfma_f32_16x16x32_bf16 v[84:87], v[64:67], v[184:187], 0
	v_mfma_f32_16x16x32_bf16 v[76:79], v[136:139], v[184:187], 0
	v_mfma_f32_16x16x32_bf16 v[132:135], v[68:71], v[164:167], v[132:135]
	v_mfma_f32_16x16x32_bf16 v[128:131], v[140:143], v[164:167], v[128:131]
	v_mfma_f32_16x16x32_bf16 v[116:119], v[68:71], v[172:175], v[116:119]
	v_mfma_f32_16x16x32_bf16 v[108:111], v[140:143], v[172:175], v[108:111]
	v_mfma_f32_16x16x32_bf16 v[100:103], v[68:71], v[180:183], v[100:103]
	v_mfma_f32_16x16x32_bf16 v[92:95], v[140:143], v[180:183], v[92:95]
	v_mfma_f32_16x16x32_bf16 v[84:87], v[68:71], v[188:191], v[84:87]
	v_mfma_f32_16x16x32_bf16 v[76:79], v[140:143], v[188:191], v[76:79]
	v_mfma_f32_16x16x32_bf16 v[124:127], v[144:147], v[160:163], 0
	v_mfma_f32_16x16x32_bf16 v[120:123], v[152:155], v[160:163], 0
	v_mfma_f32_16x16x32_bf16 v[112:115], v[144:147], v[168:171], 0
	v_mfma_f32_16x16x32_bf16 v[104:107], v[152:155], v[168:171], 0
	v_mfma_f32_16x16x32_bf16 v[96:99], v[144:147], v[176:179], 0
	v_mfma_f32_16x16x32_bf16 v[88:91], v[152:155], v[176:179], 0
	v_mfma_f32_16x16x32_bf16 v[80:83], v[144:147], v[184:187], 0
	v_mfma_f32_16x16x32_bf16 v[72:75], v[152:155], v[184:187], 0
	v_mfma_f32_16x16x32_bf16 v[124:127], v[148:151], v[164:167], v[124:127]
	v_mfma_f32_16x16x32_bf16 v[120:123], v[156:159], v[164:167], v[120:123]
	v_mfma_f32_16x16x32_bf16 v[112:115], v[148:151], v[172:175], v[112:115]
	v_mfma_f32_16x16x32_bf16 v[104:107], v[156:159], v[172:175], v[104:107]
	v_mfma_f32_16x16x32_bf16 v[96:99], v[148:151], v[180:183], v[96:99]
	v_mfma_f32_16x16x32_bf16 v[88:91], v[156:159], v[180:183], v[88:91]
	v_mfma_f32_16x16x32_bf16 v[80:83], v[148:151], v[188:191], v[80:83]
	v_mfma_f32_16x16x32_bf16 v[72:75], v[156:159], v[188:191], v[72:75]
	s_setprio 0
	s_barrier
	s_add_i32 s18, s64, s95
	s_mov_b32 m0, s18
	ds_read_b128 v[160:163], v245 offset:16384
	ds_read_b128 v[164:167], v245 offset:17408
	ds_read_b128 v[168:171], v245 offset:18432
	ds_read_b128 v[172:175], v245 offset:19456
	ds_read_b128 v[176:179], v245 offset:20480
	ds_read_b128 v[180:183], v245 offset:21504
	ds_read_b128 v[184:187], v245 offset:22528
	ds_read_b128 v[188:191], v245 offset:23552
	global_load_lds_dwordx4 v218, s[56:57]
	s_add_i32 m0, s18, 0x2000
	s_add_u32 s18, s56, 0x40000
	s_addc_u32 s19, s57, 0
	s_add_i32 s64, s65, s95
	global_load_lds_dwordx4 v222, s[56:57]
	s_mov_b32 m0, s64
	s_nop 0
	global_load_lds_dwordx4 v218, s[18:19]
	s_add_i32 m0, s64, 0x2000
	s_nop 0
	global_load_lds_dwordx4 v222, s[18:19]
	s_mov_b32 m0, s33
	s_nop 0
	global_load_lds_dwordx4 v216, s[58:59]
	s_mov_b32 m0, s82
	s_nop 0
	global_load_lds_dwordx4 v220, s[58:59]
	s_waitcnt vmcnt(8)
	s_waitcnt lgkmcnt(0)
	s_barrier
; #define PG8_STAGE(bufoff, gbase, voff) do { _Pragma("unroll") for (int _i = 0; _i < 2; ++_i) \
;         __builtin_amdgcn_global_load_lds((const unsigned*)((const char*)(gbase) + (voff)[_i]), (PG8_LAS unsigned*)(lds + (bufoff) + ldsw + _i * 8192), 16, 0, 0); } while (0)
; #define PG8_LDA(dst, b, h) do { _Pragma("unroll") for (int m = 0; m < 4; ++m) _Pragma("unroll") for (int k = 0; k < 2; ++k) dst[m][k] = *(const PG8_LAS bf16x8*)(lds + PG8_SA(b, h) + aoff + m * 2048 + k * 1024); } while (0)
; #define PG8_LDB(dst, b, h) do { _Pragma("unroll") for (int n = 0; n < 2; ++n) _Pragma("unroll") for (int k = 0; k < 2; ++k) dst[n][k] = *(const PG8_LAS bf16x8*)(lds + PG8_SB(b, h) + boff + n * 2048 + k * 1024); } while (0)
; #define PG8_MMA(ai, bj, At, Bt) do { __builtin_amdgcn_s_setprio(1); _Pragma("unroll") for (int m = 0; m < 4; ++m) _Pragma("unroll") for (int n = 0; n < 2; ++n) _Pragma("unroll") for (int k = 0; k < 2; ++k) \
;         acc[ai][bj][m][n] = __builtin_amdgcn_mfma_f32_16x16x32_bf16(Bt[n][k], At[m][k], acc[ai][bj][m][n], 0, 0, 0); __builtin_amdgcn_s_setprio(0); } while (0)
; #define PG8_WAIT_V(n) asm volatile("s_waitcnt vmcnt(" #n ")" ::: "memory")
; #define PG8_WAIT_L(n) asm volatile("s_waitcnt lgkmcnt(" #n ")" ::: "memory")
; #define PG8_BAR __builtin_amdgcn_s_barrier()
; #define PG8_SCHED __builtin_amdgcn_sched_barrier(0)
; template <class Epi, class Sched, bool ALIGN_EPI = false, bool SP2 = false>
; __device__ __forceinline__ void gemm_phase(PG8_LAS unsigned char* lds, const Gemm g, const Sched& S, const Epi& E, const int wave0) {
;     ...
;             PG8_WAIT_V(8); PG8_WAIT_L(0); PG8_BAR; PG8_MMA(0, 0, At, B0); PG8_MMA(0, 1, At, B1); PG8_BAR; PG8_SCHED;
;             PG8_LDA(At, 0, 1); PG8_STAGE(PG8_SB(0, 0), b2, voffB); PG8_STAGE(PG8_SB(0, 1), b2 + hstep, voffB); PG8_STAGE(PG8_SA(0, 0), a2, voffA);
;             PG8_WAIT_V(8); PG8_WAIT_L(0); PG8_BAR; PG8_MMA(1, 0, At, B0); PG8_MMA(1, 1, At, B1); PG8_BAR; PG8_SCHED;
;             PG8_LDB(B0, 1, 0); PG8_LDB(B1, 1, 1); PG8_SCHED; PG8_LDA(At, 1, 0); PG8_STAGE(PG8_SA(0, 1), a2 + hstep, voffA);
;             PG8_WAIT_V(8); PG8_WAIT_L(0); PG8_BAR; PG8_MMA(0, 0, At, B0); PG8_MMA(0, 1, At, B1); PG8_BAR; PG8_SCHED;
	s_setprio 1
	v_mfma_f32_16x16x32_bf16 v[60:63], v[64:67], v[160:163], 0
	v_mfma_f32_16x16x32_bf16 v[52:55], v[136:139], v[160:163], 0
	v_mfma_f32_16x16x32_bf16 v[44:47], v[64:67], v[168:171], 0
	v_mfma_f32_16x16x32_bf16 v[36:39], v[136:139], v[168:171], 0
	v_mfma_f32_16x16x32_bf16 v[28:31], v[64:67], v[176:179], 0
	v_mfma_f32_16x16x32_bf16 v[20:23], v[136:139], v[176:179], 0
	v_mfma_f32_16x16x32_bf16 v[12:15], v[64:67], v[184:187], 0
	v_mfma_f32_16x16x32_bf16 v[4:7], v[136:139], v[184:187], 0
	v_mfma_f32_16x16x32_bf16 v[60:63], v[68:71], v[164:167], v[60:63]
	v_mfma_f32_16x16x32_bf16 v[52:55], v[140:143], v[164:167], v[52:55]
	v_mfma_f32_16x16x32_bf16 v[44:47], v[68:71], v[172:175], v[44:47]
	v_mfma_f32_16x16x32_bf16 v[36:39], v[140:143], v[172:175], v[36:39]
	v_mfma_f32_16x16x32_bf16 v[28:31], v[68:71], v[180:183], v[28:31]
	v_mfma_f32_16x16x32_bf16 v[20:23], v[140:143], v[180:183], v[20:23]
	v_mfma_f32_16x16x32_bf16 v[12:15], v[68:71], v[188:191], v[12:15]
	v_mfma_f32_16x16x32_bf16 v[4:7], v[140:143], v[188:191], v[4:7]
	v_mfma_f32_16x16x32_bf16 v[56:59], v[144:147], v[160:163], 0
	v_mfma_f32_16x16x32_bf16 v[48:51], v[152:155], v[160:163], 0
	v_mfma_f32_16x16x32_bf16 v[40:43], v[144:147], v[168:171], 0
	v_mfma_f32_16x16x32_bf16 v[32:35], v[152:155], v[168:171], 0
	v_mfma_f32_16x16x32_bf16 v[24:27], v[144:147], v[176:179], 0
	v_mfma_f32_16x16x32_bf16 v[16:19], v[152:155], v[176:179], 0
	v_mfma_f32_16x16x32_bf16 v[8:11], v[144:147], v[184:187], 0
	v_mfma_f32_16x16x32_bf16 v[0:3], v[152:155], v[184:187], 0
	v_mfma_f32_16x16x32_bf16 v[56:59], v[148:151], v[164:167], v[56:59]
	v_mfma_f32_16x16x32_bf16 v[48:51], v[156:159], v[164:167], v[48:51]
	v_mfma_f32_16x16x32_bf16 v[40:43], v[148:151], v[172:175], v[40:43]
	v_mfma_f32_16x16x32_bf16 v[32:35], v[156:159], v[172:175], v[32:35]
	v_mfma_f32_16x16x32_bf16 v[24:27], v[148:151], v[180:183], v[24:27]
	v_mfma_f32_16x16x32_bf16 v[16:19], v[156:159], v[180:183], v[16:19]
	v_mfma_f32_16x16x32_bf16 v[8:11], v[148:151], v[188:191], v[8:11]
	v_mfma_f32_16x16x32_bf16 v[0:3], v[156:159], v[188:191], v[0:3]
	s_setprio 0
	s_barrier
	s_add_i32 s64, 0, 0x18000
	s_add_i32 s65, 0, 0x1c000
	v_add_u32_e32 v140, s64, v247
	v_add_u32_e32 v156, s65, v247
	ds_read_b128 v[64:67], v140
	ds_read_b128 v[68:71], v140 offset:1024
	ds_read_b128 v[136:139], v140 offset:2048
	ds_read_b128 v[140:143], v140 offset:3072
	ds_read_b128 v[144:147], v156
	ds_read_b128 v[148:151], v156 offset:1024
	ds_read_b128 v[152:155], v156 offset:2048
	ds_read_b128 v[156:159], v156 offset:3072
	s_add_u32 s18, s58, 0x40000
	s_addc_u32 s19, s59, 0
	s_mov_b32 m0, s16
	ds_read_b128 v[160:163], v245 offset:32768
	ds_read_b128 v[164:167], v245 offset:33792
	ds_read_b128 v[168:171], v245 offset:34816
	ds_read_b128 v[172:175], v245 offset:35840
	ds_read_b128 v[176:179], v245 offset:36864
	ds_read_b128 v[180:183], v245 offset:37888
	ds_read_b128 v[184:187], v245 offset:38912
	ds_read_b128 v[188:191], v245 offset:39936
	global_load_lds_dwordx4 v216, s[18:19]
	s_mov_b32 m0, s83
	s_nop 0
	global_load_lds_dwordx4 v220, s[18:19]
	s_waitcnt vmcnt(8)
	s_waitcnt lgkmcnt(0)
	s_barrier
	s_setprio 1
	v_mfma_f32_16x16x32_bf16 v[132:135], v[64:67], v[160:163], v[132:135]
	v_mfma_f32_16x16x32_bf16 v[128:131], v[136:139], v[160:163], v[128:131]
	v_mfma_f32_16x16x32_bf16 v[116:119], v[64:67], v[168:171], v[116:119]
	v_mfma_f32_16x16x32_bf16 v[108:111], v[136:139], v[168:171], v[108:111]
	v_mfma_f32_16x16x32_bf16 v[100:103], v[64:67], v[176:179], v[100:103]
	v_mfma_f32_16x16x32_bf16 v[92:95], v[136:139], v[176:179], v[92:95]
	v_mfma_f32_16x16x32_bf16 v[84:87], v[64:67], v[184:187], v[84:87]
	v_mfma_f32_16x16x32_bf16 v[76:79], v[136:139], v[184:187], v[76:79]
	v_mfma_f32_16x16x32_bf16 v[132:135], v[68:71], v[164:167], v[132:135]
	v_mfma_f32_16x16x32_bf16 v[128:131], v[140:143], v[164:167], v[128:131]
	v_mfma_f32_16x16x32_bf16 v[116:119], v[68:71], v[172:175], v[116:119]
	v_mfma_f32_16x16x32_bf16 v[108:111], v[140:143], v[172:175], v[108:111]
	v_mfma_f32_16x16x32_bf16 v[100:103], v[68:71], v[180:183], v[100:103]
	v_mfma_f32_16x16x32_bf16 v[92:95], v[140:143], v[180:183], v[92:95]
	v_mfma_f32_16x16x32_bf16 v[84:87], v[68:71], v[188:191], v[84:87]
	v_mfma_f32_16x16x32_bf16 v[76:79], v[140:143], v[188:191], v[76:79]
	v_mfma_f32_16x16x32_bf16 v[124:127], v[144:147], v[160:163], v[124:127]
	v_mfma_f32_16x16x32_bf16 v[120:123], v[152:155], v[160:163], v[120:123]
	v_mfma_f32_16x16x32_bf16 v[112:115], v[144:147], v[168:171], v[112:115]
	v_mfma_f32_16x16x32_bf16 v[104:107], v[152:155], v[168:171], v[104:107]
	v_mfma_f32_16x16x32_bf16 v[96:99], v[144:147], v[176:179], v[96:99]
	v_mfma_f32_16x16x32_bf16 v[88:91], v[152:155], v[176:179], v[88:91]
	v_mfma_f32_16x16x32_bf16 v[80:83], v[144:147], v[184:187], v[80:83]
	v_mfma_f32_16x16x32_bf16 v[72:75], v[152:155], v[184:187], v[72:75]
	v_mfma_f32_16x16x32_bf16 v[124:127], v[148:151], v[164:167], v[124:127]
	v_mfma_f32_16x16x32_bf16 v[120:123], v[156:159], v[164:167], v[120:123]
	v_mfma_f32_16x16x32_bf16 v[112:115], v[148:151], v[172:175], v[112:115]
	v_mfma_f32_16x16x32_bf16 v[104:107], v[156:159], v[172:175], v[104:107]
	v_mfma_f32_16x16x32_bf16 v[96:99], v[148:151], v[180:183], v[96:99]
	v_mfma_f32_16x16x32_bf16 v[88:91], v[156:159], v[180:183], v[88:91]
	v_mfma_f32_16x16x32_bf16 v[80:83], v[148:151], v[188:191], v[80:83]
	v_mfma_f32_16x16x32_bf16 v[72:75], v[156:159], v[188:191], v[72:75]
	s_setprio 0
	s_barrier
; #define PG8_STAGE(bufoff, gbase, voff) do { _Pragma("unroll") for (int _i = 0; _i < 2; ++_i) \
;         __builtin_amdgcn_global_load_lds((const unsigned*)((const char*)(gbase) + (voff)[_i]), (PG8_LAS unsigned*)(lds + (bufoff) + ldsw + _i * 8192), 16, 0, 0); } while (0)
; #define PG8_LDA(dst, b, h) do { _Pragma("unroll") for (int m = 0; m < 4; ++m) _Pragma("unroll") for (int k = 0; k < 2; ++k) dst[m][k] = *(const PG8_LAS bf16x8*)(lds + PG8_SA(b, h) + aoff + m * 2048 + k * 1024); } while (0)
; #define PG8_LDB(dst, b, h) do { _Pragma("unroll") for (int n = 0; n < 2; ++n) _Pragma("unroll") for (int k = 0; k < 2; ++k) dst[n][k] = *(const PG8_LAS bf16x8*)(lds + PG8_SB(b, h) + boff + n * 2048 + k * 1024); } while (0)
; #define PG8_MMA(ai, bj, At, Bt) do { __builtin_amdgcn_s_setprio(1); _Pragma("unroll") for (int m = 0; m < 4; ++m) _Pragma("unroll") for (int n = 0; n < 2; ++n) _Pragma("unroll") for (int k = 0; k < 2; ++k) \
;         acc[ai][bj][m][n] = __builtin_amdgcn_mfma_f32_16x16x32_bf16(Bt[n][k], At[m][k], acc[ai][bj][m][n], 0, 0, 0); __builtin_amdgcn_s_setprio(0); } while (0)
; #define PG8_WAIT_V(n) asm volatile("s_waitcnt vmcnt(" #n ")" ::: "memory")
; #define PG8_WAIT_L(n) asm volatile("s_waitcnt lgkmcnt(" #n ")" ::: "memory")
; #define PG8_BAR __builtin_amdgcn_s_barrier()
; #define PG8_SCHED __builtin_amdgcn_sched_barrier(0)
; template <class Epi, class Sched, bool ALIGN_EPI = false, bool SP2 = false>
; __device__ __forceinline__ void gemm_phase(PG8_LAS unsigned char* lds, const Gemm g, const Sched& S, const Epi& E, const int wave0) {
;     ...
;             PG8_LDB(B0, 1, 0); PG8_LDB(B1, 1, 1); PG8_SCHED; PG8_LDA(At, 1, 0); PG8_STAGE(PG8_SA(0, 1), a2 + hstep, voffA);
;             PG8_WAIT_V(8); PG8_WAIT_L(0); PG8_BAR; PG8_MMA(0, 0, At, B0); PG8_MMA(0, 1, At, B1); PG8_BAR; PG8_SCHED;
;             PG8_LDA(At, 1, 1); PG8_STAGE(PG8_SB(1, 0), b3, voffB); PG8_STAGE(PG8_SB(1, 1), b3 + hstep, voffB); PG8_STAGE(PG8_SA(1, 0), a3, voffA);
;             PG8_WAIT_V(8); PG8_WAIT_L(0); PG8_BAR; PG8_MMA(1, 0, At, B0); PG8_MMA(1, 1, At, B1); PG8_BAR; PG8_SCHED;
	s_add_i32 s18, s64, s95
	s_add_i32 m0, s18, 0xffffff80
	ds_read_b128 v[160:163], v245 offset:49152
	ds_read_b128 v[164:167], v245 offset:50176
	ds_read_b128 v[168:171], v245 offset:51200
	ds_read_b128 v[172:175], v245 offset:52224
	ds_read_b128 v[176:179], v245 offset:53248
	ds_read_b128 v[180:183], v245 offset:54272
	ds_read_b128 v[184:187], v245 offset:55296
	ds_read_b128 v[188:191], v245 offset:56320
	global_load_lds_dwordx4 v218, s[56:57] offset:128
	s_add_i32 m0, s18, 0x1f80
	s_add_u32 s18, s56, 0x40080
	s_addc_u32 s19, s57, 0
	global_load_lds_dwordx4 v222, s[56:57] offset:128
	s_add_i32 s56, s65, s95
	s_mov_b32 m0, s56
	s_nop 0
	global_load_lds_dwordx4 v218, s[18:19]
	s_add_i32 m0, s56, 0x2000
	s_nop 0
	global_load_lds_dwordx4 v222, s[18:19]
	s_add_i32 m0, s17, 0xffffff80
	s_nop 0
	global_load_lds_dwordx4 v216, s[58:59] offset:128
	s_add_i32 m0, s23, 0xffffff80
	s_nop 0
	global_load_lds_dwordx4 v220, s[58:59] offset:128
	s_waitcnt vmcnt(8)
	s_waitcnt lgkmcnt(0)
	s_barrier
	s_setprio 1
	v_mfma_f32_16x16x32_bf16 v[60:63], v[64:67], v[160:163], v[60:63]
	v_mfma_f32_16x16x32_bf16 v[52:55], v[136:139], v[160:163], v[52:55]
	v_mfma_f32_16x16x32_bf16 v[44:47], v[64:67], v[168:171], v[44:47]
	v_mfma_f32_16x16x32_bf16 v[36:39], v[136:139], v[168:171], v[36:39]
	v_mfma_f32_16x16x32_bf16 v[28:31], v[64:67], v[176:179], v[28:31]
	v_mfma_f32_16x16x32_bf16 v[20:23], v[136:139], v[176:179], v[20:23]
	v_mfma_f32_16x16x32_bf16 v[12:15], v[64:67], v[184:187], v[12:15]
	v_mfma_f32_16x16x32_bf16 v[4:7], v[136:139], v[184:187], v[4:7]
	v_mfma_f32_16x16x32_bf16 v[60:63], v[68:71], v[164:167], v[60:63]
	v_mfma_f32_16x16x32_bf16 v[52:55], v[140:143], v[164:167], v[52:55]
	v_mfma_f32_16x16x32_bf16 v[44:47], v[68:71], v[172:175], v[44:47]
	v_mfma_f32_16x16x32_bf16 v[36:39], v[140:143], v[172:175], v[36:39]
	v_mfma_f32_16x16x32_bf16 v[28:31], v[68:71], v[180:183], v[28:31]
	v_mfma_f32_16x16x32_bf16 v[20:23], v[140:143], v[180:183], v[20:23]
	v_mfma_f32_16x16x32_bf16 v[12:15], v[68:71], v[188:191], v[12:15]
	v_mfma_f32_16x16x32_bf16 v[4:7], v[140:143], v[188:191], v[4:7]
	v_mfma_f32_16x16x32_bf16 v[56:59], v[144:147], v[160:163], v[56:59]
	v_mfma_f32_16x16x32_bf16 v[48:51], v[152:155], v[160:163], v[48:51]
	v_mfma_f32_16x16x32_bf16 v[40:43], v[144:147], v[168:171], v[40:43]
	v_mfma_f32_16x16x32_bf16 v[32:35], v[152:155], v[168:171], v[32:35]
	v_mfma_f32_16x16x32_bf16 v[24:27], v[144:147], v[176:179], v[24:27]
	v_mfma_f32_16x16x32_bf16 v[16:19], v[152:155], v[176:179], v[16:19]
	v_mfma_f32_16x16x32_bf16 v[8:11], v[144:147], v[184:187], v[8:11]
	v_mfma_f32_16x16x32_bf16 v[0:3], v[152:155], v[184:187], v[0:3]
	v_mfma_f32_16x16x32_bf16 v[56:59], v[148:151], v[164:167], v[56:59]
	v_mfma_f32_16x16x32_bf16 v[48:51], v[156:159], v[164:167], v[48:51]
	v_mfma_f32_16x16x32_bf16 v[40:43], v[148:151], v[172:175], v[40:43]
	v_mfma_f32_16x16x32_bf16 v[32:35], v[156:159], v[172:175], v[32:35]
	v_mfma_f32_16x16x32_bf16 v[24:27], v[148:151], v[180:183], v[24:27]
	v_mfma_f32_16x16x32_bf16 v[16:19], v[156:159], v[180:183], v[16:19]
	v_mfma_f32_16x16x32_bf16 v[8:11], v[148:151], v[188:191], v[8:11]
	v_mfma_f32_16x16x32_bf16 v[0:3], v[156:159], v[188:191], v[0:3]
	s_setprio 0
	s_barrier
	s_add_i32 s63, s63, 2
	s_add_u32 s10, s10, 0x100
	s_addc_u32 s11, s11, 0
	s_add_u32 s61, s61, 0x100
	s_addc_u32 s62, s62, 0
	s_cmp_gt_u32 s63, 13

; __device__ __forceinline__ unsigned cvtpk(float lo, float hi) { f32x2 v = {lo, hi}; bf16x2_t b = __builtin_convertvector(v, bf16x2_t); return __builtin_bit_cast(unsigned, b); }
; __device__ __forceinline__ float silu_f(float x) { return x * __builtin_amdgcn_rcpf(1.0f + __builtin_amdgcn_exp2f(-LOG2E * x)); }
;     __device__ __forceinline__ void operator()(const pg8::f32x4 (&acc)[2][2][4][2], const pg8::Unit& u, int wr, int wc, int fr, int fq) const {
;     ...
;         if (kind == EK_ACT) {
;             float rsv[2][4];
; #pragma unroll
;             for (int ai = 0; ai < 2; ++ai)
; #pragma unroll
;                 for (int m = 0; m < 4; ++m) rsv[ai][m] = fin[rowb + 128 * ai + 16 * m];
; #pragma unroll
;             for (int ai = 0; ai < 2; ++ai)
; #pragma unroll
;                 for (int m = 0; m < 4; ++m) {
;                     bf16_t* rp = o0 + (size_t)(rowb + 128 * ai + 16 * m) * ldc + u.pn * 128 + wc * 32 + (PERM ? 8 : 4) * fq;
;                     const float rs = __builtin_amdgcn_rsqf(rsv[ai][m] * (1.0f / DM) + EPS);
;                     u32x2 wn[2];
; #pragma unroll
;                     for (int n = 0; n < 2; ++n) {
;                         const pg8::f32x4 g = acc[ai][0][m][n] * rs, up = acc[ai][1][m][n] * rs;
;                         wn[n].x = cvtpk(silu_f(g[0]) * up[0], silu_f(g[1]) * up[1]); wn[n].y = cvtpk(silu_f(g[2]) * up[2], silu_f(g[3]) * up[3]);
;                     }
;                     if (PERM) { *(u32x4*)rp = (u32x4){wn[0].x, wn[0].y, wn[1].x, wn[1].y}; }
;                     else { *(u32x2*)rp = wn[0]; *(u32x2*)(rp + 16) = wn[1]; }
;                 }
.LBB0_1240:
	v_ashrrev_i32_e32 v229, 31, v228
	v_lshl_add_u64 v[66:67], v[228:229], 2, v[136:137]
	v_mad_i64_i32 v[66:67], s[8:9], v65, v228, 0
	s_lshl_b32 s8, s54, 7
	s_ashr_i32 s9, s8, 31
	v_lshl_add_u64 v[66:67], v[66:67], 1, v[68:69]
	s_lshl_b64 s[8:9], s[8:9], 1
	v_readlane_b32 s10, v253, 13
	v_lshl_add_u64 v[66:67], v[66:67], 0, s[8:9]
	s_lshl_b32 s80, s10, 1
	v_lshl_add_u64 v[66:67], v[66:67], 0, s[80:81]
	v_or_b32_e32 v148, 16, v228
	v_lshl_add_u64 v[66:67], v[66:67], 0, v[214:215]
	v_or_b32_e32 v147, 32, v228
	v_or_b32_e32 v145, 48, v228
	v_add_u32_e32 v143, 0x80, v228
	v_add_u32_e32 v141, 0x90, v228
	v_add_u32_e32 v139, 0xa0, v228
	v_add_u32_e32 v137, 0xb0, v228
	v_fmamk_f32 v64, v204, 0x3a800000, v244
	v_rsq_f32_e32 v64, v64
	s_nop 0
	v_pk_mul_f32 v[132:133], v[132:133], v[64:65] op_sel_hi:[1,0]
	v_pk_mul_f32 v[70:71], v[134:135], v[64:65] op_sel_hi:[1,0]
	v_mul_f32_e32 v134, 0xbfb8aa3b, v132
	v_mul_f32_e32 v135, 0xbfb8aa3b, v133
	v_exp_f32_e32 v134, v134
	v_exp_f32_e32 v135, v135
	v_pk_mul_f32 v[124:125], v[124:125], v[64:65] op_sel_hi:[1,0]
	v_pk_mul_f32 v[126:127], v[126:127], v[64:65] op_sel_hi:[1,0]
	v_add_f32_e32 v134, 1.0, v134
	v_add_f32_e32 v135, 1.0, v135
	v_rcp_f32_e32 v134, v134
	v_rcp_f32_e32 v135, v135
	v_pk_mul_f32 v[122:123], v[122:123], v[64:65] op_sel_hi:[1,0]
	v_pk_mul_f32 v[120:121], v[120:121], v[64:65] op_sel_hi:[1,0]
	v_pk_mul_f32 v[132:133], v[132:133], v[134:135]
	s_nop 0
	v_pk_mul_f32 v[124:125], v[124:125], v[132:133]
	s_nop 0
	v_cvt_pk_bf16_f32 v124, v124, v125
	v_mul_f32_e32 v125, 0xbfb8aa3b, v70
	v_exp_f32_e32 v125, v125
	s_nop 0
	v_add_f32_e32 v125, 1.0, v125
	v_rcp_f32_e32 v132, v125
	v_mul_f32_e32 v125, 0xbfb8aa3b, v71
	v_exp_f32_e32 v125, v125
	s_nop 0
	v_add_f32_e32 v125, 1.0, v125
	v_rcp_f32_e32 v133, v125
	s_nop 0
	v_pk_mul_f32 v[70:71], v[70:71], v[132:133]
	s_nop 0
	v_pk_mul_f32 v[70:71], v[126:127], v[70:71]
	v_pk_mul_f32 v[126:127], v[128:129], v[64:65] op_sel_hi:[1,0]
	v_cvt_pk_bf16_f32 v125, v70, v71
	v_pk_mul_f32 v[70:71], v[130:131], v[64:65] op_sel_hi:[1,0]
	v_mul_f32_e32 v64, 0xbfb8aa3b, v126
	v_exp_f32_e32 v64, v64
	s_nop 0
	v_add_f32_e32 v64, 1.0, v64
	v_rcp_f32_e32 v128, v64
	v_mul_f32_e32 v64, 0xbfb8aa3b, v127
	v_exp_f32_e32 v64, v64
	s_nop 0
	v_add_f32_e32 v64, 1.0, v64
	v_rcp_f32_e32 v129, v64
	v_mul_f32_e32 v64, 0xbfb8aa3b, v70
	v_exp_f32_e32 v64, v64
	v_pk_mul_f32 v[126:127], v[126:127], v[128:129]
	s_nop 0
	v_pk_mul_f32 v[120:121], v[120:121], v[126:127]
	v_add_f32_e32 v64, 1.0, v64
	v_cvt_pk_bf16_f32 v126, v120, v121
	v_rcp_f32_e32 v120, v64
	v_mul_f32_e32 v64, 0xbfb8aa3b, v71
	v_exp_f32_e32 v64, v64
	s_nop 0
	v_add_f32_e32 v64, 1.0, v64
	v_rcp_f32_e32 v121, v64
	v_fmamk_f32 v64, v205, 0x3a800000, v244
	v_rsq_f32_e32 v64, v64
	v_pk_mul_f32 v[70:71], v[70:71], v[120:121]
	s_nop 0
	v_pk_mul_f32 v[70:71], v[122:123], v[70:71]
	v_pk_mul_f32 v[116:117], v[116:117], v[64:65] op_sel_hi:[1,0]
	v_cvt_pk_bf16_f32 v127, v70, v71
	v_pk_mul_f32 v[70:71], v[118:119], v[64:65] op_sel_hi:[1,0]
	v_mul_f32_e32 v118, 0xbfb8aa3b, v116
	v_mul_f32_e32 v119, 0xbfb8aa3b, v117
	v_exp_f32_e32 v118, v118
	v_exp_f32_e32 v119, v119
	v_pk_mul_f32 v[112:113], v[112:113], v[64:65] op_sel_hi:[1,0]
	v_pk_mul_f32 v[114:115], v[114:115], v[64:65] op_sel_hi:[1,0]
	v_add_f32_e32 v118, 1.0, v118
	v_add_f32_e32 v119, 1.0, v119
	v_rcp_f32_e32 v118, v118
	v_rcp_f32_e32 v119, v119
	v_pk_mul_f32 v[108:109], v[108:109], v[64:65] op_sel_hi:[1,0]
	v_pk_mul_f32 v[106:107], v[106:107], v[64:65] op_sel_hi:[1,0]
	v_pk_mul_f32 v[104:105], v[104:105], v[64:65] op_sel_hi:[1,0]
	v_pk_mul_f32 v[116:117], v[116:117], v[118:119]
	global_store_dwordx4 v[66:67], v[124:127], off
	v_pk_mul_f32 v[112:113], v[112:113], v[116:117]
	v_mad_i64_i32 v[66:67], s[10:11], v65, v148, 0
	v_cvt_pk_bf16_f32 v112, v112, v113
	v_mul_f32_e32 v113, 0xbfb8aa3b, v70
	v_exp_f32_e32 v113, v113
	v_lshl_add_u64 v[66:67], v[66:67], 1, v[68:69]
	v_lshl_add_u64 v[66:67], v[66:67], 0, s[8:9]
	v_lshl_add_u64 v[66:67], v[66:67], 0, s[80:81]
	v_add_f32_e32 v113, 1.0, v113
	v_rcp_f32_e32 v116, v113
	v_mul_f32_e32 v113, 0xbfb8aa3b, v71
	v_exp_f32_e32 v113, v113
	v_lshl_add_u64 v[66:67], v[66:67], 0, v[214:215]
	v_add_f32_e32 v113, 1.0, v113
	v_rcp_f32_e32 v117, v113
	s_nop 0
	v_pk_mul_f32 v[70:71], v[70:71], v[116:117]
	s_nop 0
	v_pk_mul_f32 v[70:71], v[114:115], v[70:71]
	s_nop 0
	v_cvt_pk_bf16_f32 v113, v70, v71
	v_pk_mul_f32 v[70:71], v[110:111], v[64:65] op_sel_hi:[1,0]
	v_mul_f32_e32 v64, 0xbfb8aa3b, v108
	v_exp_f32_e32 v64, v64
	s_nop 0
	v_add_f32_e32 v64, 1.0, v64
	v_rcp_f32_e32 v110, v64
	v_mul_f32_e32 v64, 0xbfb8aa3b, v109
	v_exp_f32_e32 v64, v64
	s_nop 0
	v_add_f32_e32 v64, 1.0, v64
	v_rcp_f32_e32 v111, v64
	v_mul_f32_e32 v64, 0xbfb8aa3b, v70
	v_exp_f32_e32 v64, v64
	v_pk_mul_f32 v[108:109], v[108:109], v[110:111]
	s_nop 0
	v_pk_mul_f32 v[104:105], v[104:105], v[108:109]
	v_add_f32_e32 v64, 1.0, v64
	v_cvt_pk_bf16_f32 v114, v104, v105
	v_rcp_f32_e32 v104, v64
	v_mul_f32_e32 v64, 0xbfb8aa3b, v71
	v_exp_f32_e32 v64, v64
	s_nop 0
	v_add_f32_e32 v64, 1.0, v64
	v_rcp_f32_e32 v105, v64
	v_fmamk_f32 v64, v206, 0x3a800000, v244
	v_rsq_f32_e32 v64, v64
	v_pk_mul_f32 v[70:71], v[70:71], v[104:105]
	s_nop 0
	v_pk_mul_f32 v[70:71], v[106:107], v[70:71]
	v_pk_mul_f32 v[100:101], v[100:101], v[64:65] op_sel_hi:[1,0]
	v_cvt_pk_bf16_f32 v115, v70, v71
	v_pk_mul_f32 v[70:71], v[102:103], v[64:65] op_sel_hi:[1,0]
	v_mul_f32_e32 v102, 0xbfb8aa3b, v100
	v_mul_f32_e32 v103, 0xbfb8aa3b, v101
	v_exp_f32_e32 v102, v102
	v_exp_f32_e32 v103, v103
	v_pk_mul_f32 v[96:97], v[96:97], v[64:65] op_sel_hi:[1,0]
	v_pk_mul_f32 v[98:99], v[98:99], v[64:65] op_sel_hi:[1,0]
; __device__ __forceinline__ unsigned cvtpk(float lo, float hi) { f32x2 v = {lo, hi}; bf16x2_t b = __builtin_convertvector(v, bf16x2_t); return __builtin_bit_cast(unsigned, b); }
; __device__ __forceinline__ float silu_f(float x) { return x * __builtin_amdgcn_rcpf(1.0f + __builtin_amdgcn_exp2f(-LOG2E * x)); }
;     __device__ __forceinline__ void operator()(const pg8::f32x4 (&acc)[2][2][4][2], const pg8::Unit& u, int wr, int wc, int fr, int fq) const {
;     ...
;             for (int ai = 0; ai < 2; ++ai)
; #pragma unroll
;                 for (int m = 0; m < 4; ++m) {
;                     bf16_t* rp = o0 + (size_t)(rowb + 128 * ai + 16 * m) * ldc + u.pn * 128 + wc * 32 + (PERM ? 8 : 4) * fq;
;                     const float rs = __builtin_amdgcn_rsqf(rsv[ai][m] * (1.0f / DM) + EPS);
;                     u32x2 wn[2];
; #pragma unroll
;                     for (int n = 0; n < 2; ++n) {
;                         const pg8::f32x4 g = acc[ai][0][m][n] * rs, up = acc[ai][1][m][n] * rs;
;                         wn[n].x = cvtpk(silu_f(g[0]) * up[0], silu_f(g[1]) * up[1]); wn[n].y = cvtpk(silu_f(g[2]) * up[2], silu_f(g[3]) * up[3]);
;                     }
;                     if (PERM) { *(u32x4*)rp = (u32x4){wn[0].x, wn[0].y, wn[1].x, wn[1].y}; }
;                     else { *(u32x2*)rp = wn[0]; *(u32x2*)(rp + 16) = wn[1]; }
;                 }
	v_add_f32_e32 v102, 1.0, v102
	v_add_f32_e32 v103, 1.0, v103
	v_rcp_f32_e32 v102, v102
	v_rcp_f32_e32 v103, v103
	v_pk_mul_f32 v[92:93], v[92:93], v[64:65] op_sel_hi:[1,0]
	v_pk_mul_f32 v[90:91], v[90:91], v[64:65] op_sel_hi:[1,0]
	v_pk_mul_f32 v[88:89], v[88:89], v[64:65] op_sel_hi:[1,0]
	v_pk_mul_f32 v[100:101], v[100:101], v[102:103]
	global_store_dwordx4 v[66:67], v[112:115], off
	v_pk_mul_f32 v[96:97], v[96:97], v[100:101]
	v_mad_i64_i32 v[66:67], s[10:11], v65, v147, 0
	v_cvt_pk_bf16_f32 v96, v96, v97
	v_mul_f32_e32 v97, 0xbfb8aa3b, v70
	v_exp_f32_e32 v97, v97
	v_lshl_add_u64 v[66:67], v[66:67], 1, v[68:69]
	v_lshl_add_u64 v[66:67], v[66:67], 0, s[8:9]
	v_lshl_add_u64 v[66:67], v[66:67], 0, s[80:81]
	v_add_f32_e32 v97, 1.0, v97
	v_rcp_f32_e32 v100, v97
	v_mul_f32_e32 v97, 0xbfb8aa3b, v71
	v_exp_f32_e32 v97, v97
	v_lshl_add_u64 v[66:67], v[66:67], 0, v[214:215]
	v_add_f32_e32 v97, 1.0, v97
	v_rcp_f32_e32 v101, v97
	s_nop 0
	v_pk_mul_f32 v[70:71], v[70:71], v[100:101]
	s_nop 0
	v_pk_mul_f32 v[70:71], v[98:99], v[70:71]
	s_nop 0
	v_cvt_pk_bf16_f32 v97, v70, v71
	v_pk_mul_f32 v[70:71], v[94:95], v[64:65] op_sel_hi:[1,0]
	v_mul_f32_e32 v64, 0xbfb8aa3b, v92
	v_exp_f32_e32 v64, v64
	s_nop 0
	v_add_f32_e32 v64, 1.0, v64
	v_rcp_f32_e32 v94, v64
	v_mul_f32_e32 v64, 0xbfb8aa3b, v93
	v_exp_f32_e32 v64, v64
	s_nop 0
	v_add_f32_e32 v64, 1.0, v64
	v_rcp_f32_e32 v95, v64
	v_mul_f32_e32 v64, 0xbfb8aa3b, v70
	v_exp_f32_e32 v64, v64
	v_pk_mul_f32 v[92:93], v[92:93], v[94:95]
	s_nop 0
	v_pk_mul_f32 v[88:89], v[88:89], v[92:93]
	v_add_f32_e32 v64, 1.0, v64
	v_cvt_pk_bf16_f32 v98, v88, v89
	v_rcp_f32_e32 v88, v64
	v_mul_f32_e32 v64, 0xbfb8aa3b, v71
	v_exp_f32_e32 v64, v64
	s_nop 0
	v_add_f32_e32 v64, 1.0, v64
	v_rcp_f32_e32 v89, v64
	v_fmamk_f32 v64, v207, 0x3a800000, v244
	v_rsq_f32_e32 v64, v64
	v_pk_mul_f32 v[70:71], v[70:71], v[88:89]
	s_nop 0
	v_pk_mul_f32 v[70:71], v[90:91], v[70:71]
	v_pk_mul_f32 v[80:81], v[80:81], v[64:65] op_sel_hi:[1,0]
	v_cvt_pk_bf16_f32 v99, v70, v71
	v_pk_mul_f32 v[70:71], v[84:85], v[64:65] op_sel_hi:[1,0]
	v_pk_mul_f32 v[86:87], v[86:87], v[64:65] op_sel_hi:[1,0]
	v_mul_f32_e32 v84, 0xbfb8aa3b, v70
	v_mul_f32_e32 v85, 0xbfb8aa3b, v71
	v_exp_f32_e32 v84, v84
	v_exp_f32_e32 v85, v85
	v_pk_mul_f32 v[76:77], v[76:77], v[64:65] op_sel_hi:[1,0]
	v_pk_mul_f32 v[82:83], v[82:83], v[64:65] op_sel_hi:[1,0]
	v_add_f32_e32 v84, 1.0, v84
	v_add_f32_e32 v85, 1.0, v85
	v_rcp_f32_e32 v84, v84
	v_rcp_f32_e32 v85, v85
	v_pk_mul_f32 v[78:79], v[78:79], v[64:65] op_sel_hi:[1,0]
	v_pk_mul_f32 v[74:75], v[74:75], v[64:65] op_sel_hi:[1,0]
	v_pk_mul_f32 v[72:73], v[72:73], v[64:65] op_sel_hi:[1,0]
	v_pk_mul_f32 v[70:71], v[70:71], v[84:85]
	v_mul_f32_e32 v64, 0xbfb8aa3b, v76
	v_pk_mul_f32 v[70:71], v[80:81], v[70:71]
	v_exp_f32_e32 v64, v64
	v_cvt_pk_bf16_f32 v70, v70, v71
	v_mul_f32_e32 v71, 0xbfb8aa3b, v86
	v_exp_f32_e32 v71, v71
	v_add_f32_e32 v64, 1.0, v64
	global_store_dwordx4 v[66:67], v[96:99], off
	v_mad_i64_i32 v[66:67], s[10:11], v65, v145, 0
	v_add_f32_e32 v71, 1.0, v71
	v_rcp_f32_e32 v80, v71
	v_mul_f32_e32 v71, 0xbfb8aa3b, v87
	v_exp_f32_e32 v71, v71
	v_lshl_add_u64 v[66:67], v[66:67], 1, v[68:69]
	v_lshl_add_u64 v[66:67], v[66:67], 0, s[8:9]
	v_lshl_add_u64 v[66:67], v[66:67], 0, s[80:81]
	v_add_f32_e32 v71, 1.0, v71
	v_rcp_f32_e32 v81, v71
	v_lshl_add_u64 v[66:67], v[66:67], 0, v[214:215]
	v_pk_mul_f32 v[80:81], v[86:87], v[80:81]
	s_nop 0
	v_pk_mul_f32 v[80:81], v[82:83], v[80:81]
	s_nop 0
	v_cvt_pk_bf16_f32 v71, v80, v81
	v_rcp_f32_e32 v80, v64
	v_mul_f32_e32 v64, 0xbfb8aa3b, v77
	v_exp_f32_e32 v64, v64
	s_nop 0
	v_add_f32_e32 v64, 1.0, v64
	v_rcp_f32_e32 v81, v64
	v_mul_f32_e32 v64, 0xbfb8aa3b, v78
	v_exp_f32_e32 v64, v64
	v_pk_mul_f32 v[76:77], v[76:77], v[80:81]
	s_nop 0
	v_pk_mul_f32 v[72:73], v[72:73], v[76:77]
	v_add_f32_e32 v64, 1.0, v64
	v_rcp_f32_e32 v76, v64
	v_mul_f32_e32 v64, 0xbfb8aa3b, v79
	v_exp_f32_e32 v64, v64
	v_cvt_pk_bf16_f32 v72, v72, v73
	v_add_f32_e32 v64, 1.0, v64
	v_rcp_f32_e32 v77, v64
	v_fmamk_f32 v64, v208, 0x3a800000, v244
	v_rsq_f32_e32 v64, v64
	v_pk_mul_f32 v[76:77], v[78:79], v[76:77]
	s_nop 0
	v_pk_mul_f32 v[74:75], v[74:75], v[76:77]
	v_pk_mul_f32 v[60:61], v[60:61], v[64:65] op_sel_hi:[1,0]
	v_cvt_pk_bf16_f32 v73, v74, v75
	global_store_dwordx4 v[66:67], v[70:73], off
	v_pk_mul_f32 v[56:57], v[56:57], v[64:65] op_sel_hi:[1,0]
	v_pk_mul_f32 v[62:63], v[62:63], v[64:65] op_sel_hi:[1,0]
	v_mul_f32_e32 v70, 0xbfb8aa3b, v60
	v_mul_f32_e32 v71, 0xbfb8aa3b, v61
	v_exp_f32_e32 v70, v70
	v_exp_f32_e32 v71, v71
	v_pk_mul_f32 v[58:59], v[58:59], v[64:65] op_sel_hi:[1,0]
	v_pk_mul_f32 v[52:53], v[52:53], v[64:65] op_sel_hi:[1,0]
	v_add_f32_e32 v70, 1.0, v70
	v_add_f32_e32 v71, 1.0, v71
	v_rcp_f32_e32 v70, v70
	v_rcp_f32_e32 v71, v71
	v_pk_mul_f32 v[48:49], v[48:49], v[64:65] op_sel_hi:[1,0]
	v_pk_mul_f32 v[54:55], v[54:55], v[64:65] op_sel_hi:[1,0]
	v_pk_mul_f32 v[50:51], v[50:51], v[64:65] op_sel_hi:[1,0]
	v_pk_mul_f32 v[60:61], v[60:61], v[70:71]
	v_mad_i64_i32 v[66:67], s[10:11], v65, v143, 0
	v_pk_mul_f32 v[56:57], v[56:57], v[60:61]
	v_lshl_add_u64 v[66:67], v[66:67], 1, v[68:69]
	v_cvt_pk_bf16_f32 v56, v56, v57
	v_mul_f32_e32 v57, 0xbfb8aa3b, v62
	v_exp_f32_e32 v57, v57
	v_lshl_add_u64 v[66:67], v[66:67], 0, s[8:9]
	v_lshl_add_u64 v[66:67], v[66:67], 0, s[80:81]
	v_add_f32_e32 v57, 1.0, v57
	v_rcp_f32_e32 v60, v57
	v_mul_f32_e32 v57, 0xbfb8aa3b, v63
	v_exp_f32_e32 v57, v57
	s_nop 0
	v_add_f32_e32 v57, 1.0, v57
	v_rcp_f32_e32 v61, v57
	s_nop 0
	v_pk_mul_f32 v[60:61], v[62:63], v[60:61]
	s_nop 0
	v_pk_mul_f32 v[58:59], v[58:59], v[60:61]
	s_nop 0
	v_cvt_pk_bf16_f32 v57, v58, v59
; __device__ __forceinline__ unsigned cvtpk(float lo, float hi) { f32x2 v = {lo, hi}; bf16x2_t b = __builtin_convertvector(v, bf16x2_t); return __builtin_bit_cast(unsigned, b); }
; __device__ __forceinline__ float silu_f(float x) { return x * __builtin_amdgcn_rcpf(1.0f + __builtin_amdgcn_exp2f(-LOG2E * x)); }
;     __device__ __forceinline__ void operator()(const pg8::f32x4 (&acc)[2][2][4][2], const pg8::Unit& u, int wr, int wc, int fr, int fq) const {
;     ...
;             for (int ai = 0; ai < 2; ++ai)
; #pragma unroll
;                 for (int m = 0; m < 4; ++m) {
;                     bf16_t* rp = o0 + (size_t)(rowb + 128 * ai + 16 * m) * ldc + u.pn * 128 + wc * 32 + (PERM ? 8 : 4) * fq;
;                     const float rs = __builtin_amdgcn_rsqf(rsv[ai][m] * (1.0f / DM) + EPS);
;                     u32x2 wn[2];
; #pragma unroll
;                     for (int n = 0; n < 2; ++n) {
;                         const pg8::f32x4 g = acc[ai][0][m][n] * rs, up = acc[ai][1][m][n] * rs;
;                         wn[n].x = cvtpk(silu_f(g[0]) * up[0], silu_f(g[1]) * up[1]); wn[n].y = cvtpk(silu_f(g[2]) * up[2], silu_f(g[3]) * up[3]);
;                     }
;                     if (PERM) { *(u32x4*)rp = (u32x4){wn[0].x, wn[0].y, wn[1].x, wn[1].y}; }
;                     else { *(u32x2*)rp = wn[0]; *(u32x2*)(rp + 16) = wn[1]; }
;                 }
	v_mul_f32_e32 v58, 0xbfb8aa3b, v52
	v_mul_f32_e32 v59, 0xbfb8aa3b, v53
	v_exp_f32_e32 v58, v58
	v_exp_f32_e32 v59, v59
	v_add_f32_e32 v58, 1.0, v58
	v_add_f32_e32 v59, 1.0, v59
	v_rcp_f32_e32 v58, v58
	v_rcp_f32_e32 v59, v59
	s_nop 0
	v_pk_mul_f32 v[52:53], v[52:53], v[58:59]
	s_nop 0
	v_pk_mul_f32 v[48:49], v[48:49], v[52:53]
	s_nop 0
	v_cvt_pk_bf16_f32 v58, v48, v49
	v_mul_f32_e32 v48, 0xbfb8aa3b, v54
	v_mul_f32_e32 v49, 0xbfb8aa3b, v55
	v_exp_f32_e32 v48, v48
	v_exp_f32_e32 v49, v49
	v_add_f32_e32 v48, 1.0, v48
	v_add_f32_e32 v49, 1.0, v49
	v_rcp_f32_e32 v48, v48
	v_rcp_f32_e32 v49, v49
	s_nop 0
	v_pk_mul_f32 v[48:49], v[54:55], v[48:49]
	s_nop 0
	v_pk_mul_f32 v[48:49], v[50:51], v[48:49]
	v_fmamk_f32 v50, v209, 0x3a800000, v244
	v_rsq_f32_e32 v50, v50
	v_cvt_pk_bf16_f32 v59, v48, v49
	v_lshl_add_u64 v[48:49], v[66:67], 0, v[214:215]
	global_store_dwordx4 v[48:49], v[56:59], off
	v_pk_mul_f32 v[44:45], v[44:45], v[50:51] op_sel_hi:[1,0]
	v_pk_mul_f32 v[46:47], v[46:47], v[50:51] op_sel_hi:[1,0]
	v_pk_mul_f32 v[42:43], v[42:43], v[50:51] op_sel_hi:[1,0]
	v_pk_mul_f32 v[40:41], v[40:41], v[50:51] op_sel_hi:[1,0]
	v_mul_f32_e32 v51, 0xbfb8aa3b, v44
	v_exp_f32_e32 v51, v51
	v_mad_i64_i32 v[48:49], s[10:11], v65, v141, 0
	v_lshl_add_u64 v[48:49], v[48:49], 1, v[68:69]
	v_add_f32_e32 v51, 1.0, v51
	v_rcp_f32_e32 v52, v51
	v_mul_f32_e32 v51, 0xbfb8aa3b, v45
	v_exp_f32_e32 v51, v51
	v_lshl_add_u64 v[48:49], v[48:49], 0, s[8:9]
	v_lshl_add_u64 v[48:49], v[48:49], 0, s[80:81]
	v_add_f32_e32 v51, 1.0, v51
	v_rcp_f32_e32 v53, v51
	v_pk_mul_f32 v[36:37], v[36:37], v[50:51] op_sel_hi:[1,0]
	v_pk_mul_f32 v[32:33], v[32:33], v[50:51] op_sel_hi:[1,0]
	v_pk_mul_f32 v[38:39], v[38:39], v[50:51] op_sel_hi:[1,0]
	v_pk_mul_f32 v[44:45], v[44:45], v[52:53]
	v_pk_mul_f32 v[34:35], v[34:35], v[50:51] op_sel_hi:[1,0]
	v_pk_mul_f32 v[40:41], v[40:41], v[44:45]
	s_nop 0
	v_cvt_pk_bf16_f32 v40, v40, v41
	v_mul_f32_e32 v41, 0xbfb8aa3b, v46
	v_exp_f32_e32 v41, v41
	s_nop 0
	v_add_f32_e32 v41, 1.0, v41
	v_rcp_f32_e32 v44, v41
	v_mul_f32_e32 v41, 0xbfb8aa3b, v47
	v_exp_f32_e32 v41, v41
	s_nop 0
	v_add_f32_e32 v41, 1.0, v41
	v_rcp_f32_e32 v45, v41
	s_nop 0
	v_pk_mul_f32 v[44:45], v[46:47], v[44:45]
	s_nop 0
	v_pk_mul_f32 v[42:43], v[42:43], v[44:45]
	s_nop 0
	v_cvt_pk_bf16_f32 v41, v42, v43
	v_mul_f32_e32 v42, 0xbfb8aa3b, v36
	v_mul_f32_e32 v43, 0xbfb8aa3b, v37
	v_exp_f32_e32 v42, v42
	v_exp_f32_e32 v43, v43
	v_add_f32_e32 v42, 1.0, v42
	v_add_f32_e32 v43, 1.0, v43
	v_rcp_f32_e32 v42, v42
	v_rcp_f32_e32 v43, v43
	s_nop 0
	v_pk_mul_f32 v[36:37], v[36:37], v[42:43]
	s_nop 0
	v_pk_mul_f32 v[32:33], v[32:33], v[36:37]
	s_nop 0
	v_cvt_pk_bf16_f32 v42, v32, v33
	v_mul_f32_e32 v32, 0xbfb8aa3b, v38
	v_mul_f32_e32 v33, 0xbfb8aa3b, v39
	v_exp_f32_e32 v32, v32
	v_exp_f32_e32 v33, v33
	v_add_f32_e32 v32, 1.0, v32
	v_add_f32_e32 v33, 1.0, v33
	v_rcp_f32_e32 v32, v32
	v_rcp_f32_e32 v33, v33
	s_nop 0
	v_pk_mul_f32 v[32:33], v[38:39], v[32:33]
	s_nop 0
	v_pk_mul_f32 v[32:33], v[34:35], v[32:33]
	v_fmamk_f32 v34, v210, 0x3a800000, v244
	v_rsq_f32_e32 v34, v34
	v_cvt_pk_bf16_f32 v43, v32, v33
	v_lshl_add_u64 v[32:33], v[48:49], 0, v[214:215]
	global_store_dwordx4 v[32:33], v[40:43], off
	v_pk_mul_f32 v[28:29], v[28:29], v[34:35] op_sel_hi:[1,0]
	v_pk_mul_f32 v[30:31], v[30:31], v[34:35] op_sel_hi:[1,0]
	v_pk_mul_f32 v[26:27], v[26:27], v[34:35] op_sel_hi:[1,0]
	v_pk_mul_f32 v[24:25], v[24:25], v[34:35] op_sel_hi:[1,0]
	v_mul_f32_e32 v35, 0xbfb8aa3b, v28
	v_exp_f32_e32 v35, v35
	v_mad_i64_i32 v[32:33], s[10:11], v65, v139, 0
	v_lshl_add_u64 v[32:33], v[32:33], 1, v[68:69]
	v_add_f32_e32 v35, 1.0, v35
	v_rcp_f32_e32 v36, v35
	v_mul_f32_e32 v35, 0xbfb8aa3b, v29
	v_exp_f32_e32 v35, v35
	v_lshl_add_u64 v[32:33], v[32:33], 0, s[8:9]
	v_lshl_add_u64 v[32:33], v[32:33], 0, s[80:81]
	v_add_f32_e32 v35, 1.0, v35
	v_rcp_f32_e32 v37, v35
; __device__ __forceinline__ unsigned cvtpk(float lo, float hi) { f32x2 v = {lo, hi}; bf16x2_t b = __builtin_convertvector(v, bf16x2_t); return __builtin_bit_cast(unsigned, b); }
; __device__ __forceinline__ float silu_f(float x) { return x * __builtin_amdgcn_rcpf(1.0f + __builtin_amdgcn_exp2f(-LOG2E * x)); }
;     __device__ __forceinline__ void operator()(const pg8::f32x4 (&acc)[2][2][4][2], const pg8::Unit& u, int wr, int wc, int fr, int fq) const {
;     ...
;             for (int ai = 0; ai < 2; ++ai)
; #pragma unroll
;                 for (int m = 0; m < 4; ++m) {
;                     bf16_t* rp = o0 + (size_t)(rowb + 128 * ai + 16 * m) * ldc + u.pn * 128 + wc * 32 + (PERM ? 8 : 4) * fq;
;                     const float rs = __builtin_amdgcn_rsqf(rsv[ai][m] * (1.0f / DM) + EPS);
;                     u32x2 wn[2];
; #pragma unroll
;                     for (int n = 0; n < 2; ++n) {
;                         const pg8::f32x4 g = acc[ai][0][m][n] * rs, up = acc[ai][1][m][n] * rs;
;                         wn[n].x = cvtpk(silu_f(g[0]) * up[0], silu_f(g[1]) * up[1]); wn[n].y = cvtpk(silu_f(g[2]) * up[2], silu_f(g[3]) * up[3]);
;                     }
;                     if (PERM) { *(u32x4*)rp = (u32x4){wn[0].x, wn[0].y, wn[1].x, wn[1].y}; }
;                     else { *(u32x2*)rp = wn[0]; *(u32x2*)(rp + 16) = wn[1]; }
;                 }
	v_pk_mul_f32 v[20:21], v[20:21], v[34:35] op_sel_hi:[1,0]
	v_pk_mul_f32 v[16:17], v[16:17], v[34:35] op_sel_hi:[1,0]
	v_pk_mul_f32 v[22:23], v[22:23], v[34:35] op_sel_hi:[1,0]
	v_pk_mul_f32 v[28:29], v[28:29], v[36:37]
	v_pk_mul_f32 v[18:19], v[18:19], v[34:35] op_sel_hi:[1,0]
	v_pk_mul_f32 v[24:25], v[24:25], v[28:29]
	s_nop 0
	v_cvt_pk_bf16_f32 v24, v24, v25
	v_mul_f32_e32 v25, 0xbfb8aa3b, v30
	v_exp_f32_e32 v25, v25
	s_nop 0
	v_add_f32_e32 v25, 1.0, v25
	v_rcp_f32_e32 v28, v25
	v_mul_f32_e32 v25, 0xbfb8aa3b, v31
	v_exp_f32_e32 v25, v25
	s_nop 0
	v_add_f32_e32 v25, 1.0, v25
	v_rcp_f32_e32 v29, v25
	s_nop 0
	v_pk_mul_f32 v[28:29], v[30:31], v[28:29]
	s_nop 0
	v_pk_mul_f32 v[26:27], v[26:27], v[28:29]
	s_nop 0
	v_cvt_pk_bf16_f32 v25, v26, v27
	v_mul_f32_e32 v26, 0xbfb8aa3b, v20
	v_mul_f32_e32 v27, 0xbfb8aa3b, v21
	v_exp_f32_e32 v26, v26
	v_exp_f32_e32 v27, v27
	v_add_f32_e32 v26, 1.0, v26
	v_add_f32_e32 v27, 1.0, v27
	v_rcp_f32_e32 v26, v26
	v_rcp_f32_e32 v27, v27
	s_nop 0
	v_pk_mul_f32 v[20:21], v[20:21], v[26:27]
	s_nop 0
	v_pk_mul_f32 v[16:17], v[16:17], v[20:21]
	s_nop 0
	v_cvt_pk_bf16_f32 v26, v16, v17
	v_mul_f32_e32 v16, 0xbfb8aa3b, v22
	v_mul_f32_e32 v17, 0xbfb8aa3b, v23
	v_exp_f32_e32 v16, v16
	v_exp_f32_e32 v17, v17
	v_add_f32_e32 v16, 1.0, v16
	v_add_f32_e32 v17, 1.0, v17
	v_rcp_f32_e32 v16, v16
	v_rcp_f32_e32 v17, v17
	s_nop 0
	v_pk_mul_f32 v[16:17], v[22:23], v[16:17]
	s_nop 0
	v_pk_mul_f32 v[16:17], v[18:19], v[16:17]
	v_fmamk_f32 v18, v211, 0x3a800000, v244
	v_rsq_f32_e32 v18, v18
	v_cvt_pk_bf16_f32 v27, v16, v17
	v_lshl_add_u64 v[16:17], v[32:33], 0, v[214:215]
	global_store_dwordx4 v[16:17], v[24:27], off
	v_pk_mul_f32 v[12:13], v[12:13], v[18:19] op_sel_hi:[1,0]
	v_pk_mul_f32 v[14:15], v[14:15], v[18:19] op_sel_hi:[1,0]
	v_pk_mul_f32 v[10:11], v[10:11], v[18:19] op_sel_hi:[1,0]
	v_pk_mul_f32 v[8:9], v[8:9], v[18:19] op_sel_hi:[1,0]
	v_mul_f32_e32 v19, 0xbfb8aa3b, v12
	v_exp_f32_e32 v19, v19
	v_mad_i64_i32 v[16:17], s[10:11], v65, v137, 0
	v_lshl_add_u64 v[16:17], v[16:17], 1, v[68:69]
	v_add_f32_e32 v19, 1.0, v19
	v_rcp_f32_e32 v20, v19
	v_mul_f32_e32 v19, 0xbfb8aa3b, v13
	v_exp_f32_e32 v19, v19
	v_lshl_add_u64 v[16:17], v[16:17], 0, s[8:9]
	v_lshl_add_u64 v[16:17], v[16:17], 0, s[80:81]
	v_add_f32_e32 v19, 1.0, v19
	v_rcp_f32_e32 v21, v19
	v_pk_mul_f32 v[4:5], v[4:5], v[18:19] op_sel_hi:[1,0]
	v_pk_mul_f32 v[0:1], v[0:1], v[18:19] op_sel_hi:[1,0]
	v_pk_mul_f32 v[6:7], v[6:7], v[18:19] op_sel_hi:[1,0]
	v_pk_mul_f32 v[12:13], v[12:13], v[20:21]
	v_pk_mul_f32 v[2:3], v[2:3], v[18:19] op_sel_hi:[1,0]
	v_pk_mul_f32 v[8:9], v[8:9], v[12:13]
	s_nop 0
	v_cvt_pk_bf16_f32 v8, v8, v9
	v_mul_f32_e32 v9, 0xbfb8aa3b, v14
	v_exp_f32_e32 v9, v9
	s_nop 0
	v_add_f32_e32 v9, 1.0, v9
	v_rcp_f32_e32 v12, v9
	v_mul_f32_e32 v9, 0xbfb8aa3b, v15
	v_exp_f32_e32 v9, v9
	s_nop 0
	v_add_f32_e32 v9, 1.0, v9
	v_rcp_f32_e32 v13, v9
	s_nop 0
	v_pk_mul_f32 v[12:13], v[14:15], v[12:13]
	s_nop 0
	v_pk_mul_f32 v[10:11], v[10:11], v[12:13]
	s_nop 0
	v_cvt_pk_bf16_f32 v9, v10, v11
	v_mul_f32_e32 v10, 0xbfb8aa3b, v4
	v_mul_f32_e32 v11, 0xbfb8aa3b, v5
	v_exp_f32_e32 v10, v10
	v_exp_f32_e32 v11, v11
	v_add_f32_e32 v10, 1.0, v10
	v_add_f32_e32 v11, 1.0, v11
	v_rcp_f32_e32 v10, v10
	v_rcp_f32_e32 v11, v11
	s_nop 0
	v_pk_mul_f32 v[4:5], v[4:5], v[10:11]
	s_nop 0
	v_pk_mul_f32 v[0:1], v[0:1], v[4:5]
	s_nop 0
	v_cvt_pk_bf16_f32 v10, v0, v1
	v_mul_f32_e32 v0, 0xbfb8aa3b, v6
	v_mul_f32_e32 v1, 0xbfb8aa3b, v7
	v_exp_f32_e32 v0, v0
	v_exp_f32_e32 v1, v1
	v_add_f32_e32 v0, 1.0, v0
	v_add_f32_e32 v1, 1.0, v1
	v_rcp_f32_e32 v0, v0
	v_rcp_f32_e32 v1, v1
	s_nop 0
	v_pk_mul_f32 v[0:1], v[6:7], v[0:1]
	s_nop 0
	v_pk_mul_f32 v[0:1], v[2:3], v[0:1]
	s_nop 0
	v_cvt_pk_bf16_f32 v11, v0, v1
	v_lshl_add_u64 v[0:1], v[16:17], 0, v[214:215]
	global_store_dwordx4 v[0:1], v[8:11], off
	s_andn2_b64 vcc, exec, s[6:7]
	s_mov_b64 s[6:7], -1
	s_cbranch_vccnz .LBB0_1136
	s_branch .LBB0_1238
